# final_phase row loop: norm gains hoisted out of the loop, next row's loads prefetched one iteration ahead (vmcnt(4) past the 4 stores)
# speedup vs baseline: 1.0097x; 1.0097x over previous
; #define GAS __attribute__((address_space(1)))
; __device__ __forceinline__ int opq_tid() { int t = threadIdx.x; asm volatile("" : "+v"(t)); return t; }
; __device__ __forceinline__ float bf_lo(unsigned w) { return __uint_as_float(w << 16); }
; __device__ __forceinline__ float bf_hi(unsigned w) { return __uint_as_float(w & 0xffff0000u); }
; __device__ __forceinline__ void final_phase(const GAS bf16_t* xb, GAS float* out, const GAS float* gf, int G, int cblk) {
;     const int tid = opq_tid(), lane = tid & 63, wave = tid >> 6;
;     for (int row = cblk * 8 + wave; row < TH; row += G * 8) {
;         const GAS u32x4* xr = (const GAS u32x4*)(xb + (size_t)row * D) + lane;
;         GAS f32x4* orow = (GAS f32x4*)(out + (size_t)row * D);
;         const u32x4 w0 = xr[0], w1 = xr[64];
;         float s = wave_sum(sq8(w0) + sq8(w1));
;         const float rs = 1.f / sqrtf(s * (1.f / 1024.f) + EPS);
; #pragma unroll
;         for (int j = 0; j < 2; ++j) {
;             const u32x4 w = j ? w1 : w0;
;             const int c0 = 8 * lane + 512 * j;
;             const f32x4 ga = *(const GAS f32x4*)(gf + c0), gb = *(const GAS f32x4*)(gf + c0 + 4);
;             f32x4 oa, ob;
;             oa.x = bf_lo(w.x) * rs * ga.x; oa.y = bf_hi(w.x) * rs * ga.y; oa.z = bf_lo(w.y) * rs * ga.z; oa.w = bf_hi(w.y) * rs * ga.w;
;             ob.x = bf_lo(w.z) * rs * gb.x; ob.y = bf_hi(w.z) * rs * gb.y; ob.z = bf_lo(w.w) * rs * gb.z; ob.w = bf_hi(w.w) * rs * gb.w;
;             orow[c0 / 4] = oa; orow[c0 / 4 + 1] = ob;
;         }
;     }
; }
.LBB0_843:
	s_mov_b64 s[2:3], s[92:93]
	s_mov_b32 s6, s76
	s_mov_b32 s4, s74
	v_mov_b32_e32 v2, v242
	s_lshl_b32 s8, s4, 3
	v_ashrrev_i32_e32 v4, 6, v2
	v_add_u32_e32 v1, s8, v4
	v_cmp_gt_i32_e32 vcc, s97, v1
	s_and_saveexec_b64 s[4:5], vcc
	s_cbranch_execz .LBB0_846
	v_ashrrev_i32_e32 v5, 31, v4
	s_ashr_i32 s9, s8, 31
	v_lshl_add_u64 v[14:15], v[4:5], 0, s[8:9]
	v_and_b32_e32 v16, 63, v2
	v_lshlrev_b64 v[4:5], 11, v[14:15]
	v_lshl_or_b32 v4, v16, 4, v4
	v_cmp_lt_i32_e32 vcc, v249, v253
	v_lshl_add_u64 v[4:5], s[2:3], 0, v[4:5]
	s_mov_b64 s[2:3], 0x7b00400
	v_cndmask_b32_e32 v2, v246, v249, vcc
	v_cmp_lt_i32_e32 vcc, v250, v253
	v_lshl_add_u64 v[4:5], v[4:5], 0, s[2:3]
	v_readlane_b32 s2, v254, 32
	v_lshlrev_b32_e32 v8, 2, v2
	v_cndmask_b32_e32 v2, v246, v250, vcc
	v_cmp_lt_i32_e32 vcc, v182, v253
	v_readlane_b32 s3, v254, 33
	v_lshlrev_b32_e32 v9, 2, v2
	v_cndmask_b32_e32 v2, v246, v182, vcc
	v_cmp_lt_i32_e32 vcc, v240, v253
	s_mov_b32 s3, s91
	v_lshlrev_b32_e32 v10, 2, v2
	v_cndmask_b32_e32 v2, v246, v240, vcc
	v_cmp_lt_i32_e32 vcc, v251, v253
	s_lshl_b64 s[2:3], s[2:3], 26
	v_lshlrev_b64 v[14:15], 12, v[14:15]
	v_lshlrev_b32_e32 v11, 2, v2
	v_cndmask_b32_e32 v2, v246, v251, vcc
	v_cmp_lt_i32_e32 vcc, v252, v253
	s_lshl_b32 s6, s6, 3
	v_lshlrev_b32_e32 v6, 5, v16
	v_readlane_b32 s12, v254, 4
	v_lshl_add_u64 v[14:15], s[2:3], 0, v[14:15]
	v_readlane_b32 s2, v254, 22
	v_lshlrev_b32_e32 v12, 2, v2
	v_cndmask_b32_e32 v2, v246, v252, vcc
	v_mov_b32_e32 v7, v0
	v_readlane_b32 s13, v254, 5
	v_readlane_b32 s16, v254, 8
	v_readlane_b32 s17, v254, 9
	s_ashr_i32 s7, s6, 31
	v_or_b32_e32 v14, v14, v6
	v_readlane_b32 s3, v254, 23
	v_lshlrev_b32_e32 v13, 2, v2
	v_lshl_add_u64 v[2:3], s[16:17], 0, v[6:7]
	s_lshl_b64 s[8:9], s[6:7], 11
	v_lshl_add_u64 v[6:7], s[2:3], 0, v[14:15]
	s_lshl_b64 s[10:11], s[6:7], 12
	s_mov_b64 s[12:13], 0
	v_readlane_b32 s14, v254, 6
	v_readlane_b32 s15, v254, 7
	v_readlane_b32 s18, v254, 10
	v_readlane_b32 s19, v254, 11
	v_readlane_b32 s20, v254, 12
	v_readlane_b32 s21, v254, 13
	v_readlane_b32 s22, v254, 14
	v_readlane_b32 s23, v254, 15
	v_readlane_b32 s24, v254, 16
	v_readlane_b32 s25, v254, 17
	v_readlane_b32 s26, v254, 18
	v_readlane_b32 s27, v254, 19
	global_load_dwordx4 v[54:57], v[2:3], off
	global_load_dwordx4 v[58:61], v[2:3], off offset:16
	global_load_dwordx4 v[62:65], v[2:3], off offset:2048
	global_load_dwordx4 v[66:69], v[2:3], off offset:2064
	global_load_dwordx4 v[70:73], v[4:5], off offset:-1024
	global_load_dwordx4 v[74:77], v[4:5], off
	v_lshl_add_u64 v[4:5], v[4:5], 0, s[8:9]
	s_waitcnt vmcnt(0)
.LBB0_845:
	v_add_u32_e32 v1, s6, v1
	s_waitcnt vmcnt(4)
	v_lshlrev_b32_e32 v30, 16, v72
	v_and_b32_e32 v31, 0xffff0000, v72
	v_lshlrev_b32_e32 v16, 16, v73
	v_and_b32_e32 v17, 0xffff0000, v73
	v_lshlrev_b32_e32 v32, 16, v70
	v_and_b32_e32 v33, 0xffff0000, v70
	v_lshlrev_b32_e32 v14, 16, v71
	v_and_b32_e32 v15, 0xffff0000, v71
	v_and_b32_e32 v35, 0xffff0000, v76
	v_and_b32_e32 v37, 0xffff0000, v77
	v_and_b32_e32 v39, 0xffff0000, v74
	v_and_b32_e32 v41, 0xffff0000, v75
	v_lshlrev_b32_e32 v34, 16, v76
	v_lshlrev_b32_e32 v36, 16, v77
	v_lshlrev_b32_e32 v38, 16, v74
	v_lshlrev_b32_e32 v40, 16, v75
	global_load_dwordx4 v[70:73], v[4:5], off offset:-1024
	global_load_dwordx4 v[74:77], v[4:5], off
	v_lshl_add_u64 v[4:5], v[4:5], 0, s[8:9]
	v_mov_b32_e32 v20, v31
	v_mov_b32_e32 v21, v35
	v_mov_b32_e32 v44, v17
	v_mov_b32_e32 v45, v37
	v_mov_b32_e32 v48, v33
	v_mov_b32_e32 v49, v39
	v_mov_b32_e32 v52, v15
	v_mov_b32_e32 v53, v41
	v_mov_b32_e32 v18, v30
	v_mov_b32_e32 v19, v34
	v_mov_b32_e32 v42, v16
	v_mov_b32_e32 v43, v36
	v_mov_b32_e32 v46, v32
	v_mov_b32_e32 v47, v38
	v_mov_b32_e32 v50, v14
	v_mov_b32_e32 v51, v40
	v_pk_mul_f32 v[20:21], v[20:21], v[20:21]
	v_pk_mul_f32 v[44:45], v[44:45], v[44:45]
	v_pk_mul_f32 v[48:49], v[48:49], v[48:49]
	v_pk_mul_f32 v[52:53], v[52:53], v[52:53]
	v_pk_fma_f32 v[18:19], v[18:19], v[18:19], v[20:21]
	v_pk_fma_f32 v[20:21], v[42:43], v[42:43], v[44:45]
	v_pk_fma_f32 v[42:43], v[46:47], v[46:47], v[48:49]
	v_pk_fma_f32 v[44:45], v[50:51], v[50:51], v[52:53]
	v_pk_add_f32 v[18:19], v[18:19], v[20:21]
	v_pk_add_f32 v[20:21], v[42:43], v[44:45]
	s_nop 0
	v_pk_add_f32 v[18:19], v[20:21], v[18:19]
	s_nop 0
	v_add_f32_e32 v18, v18, v19
	ds_bpermute_b32 v19, v8, v18
	s_waitcnt lgkmcnt(0)
	v_add_f32_e32 v18, v18, v19
	ds_bpermute_b32 v19, v9, v18
	s_waitcnt lgkmcnt(0)
	v_add_f32_e32 v18, v18, v19
	ds_bpermute_b32 v19, v10, v18
	s_waitcnt lgkmcnt(0)
	v_add_f32_e32 v18, v18, v19
	ds_bpermute_b32 v19, v11, v18
	s_waitcnt lgkmcnt(0)
	v_add_f32_e32 v18, v18, v19
	ds_bpermute_b32 v19, v12, v18
	s_waitcnt lgkmcnt(0)
	v_add_f32_e32 v18, v18, v19
	ds_bpermute_b32 v19, v13, v18
	s_waitcnt lgkmcnt(0)
	v_add_f32_e32 v18, v18, v19
	v_fmamk_f32 v18, v18, 0x3a800000, v244
	v_mul_f32_e32 v19, 0x4f800000, v18
	v_cmp_gt_f32_e32 vcc, s62, v18
	s_nop 1
	v_cndmask_b32_e32 v18, v18, v19, vcc
	v_sqrt_f32_e32 v19, v18
	s_nop 0
	v_add_u32_e32 v20, -1, v19
	v_add_u32_e32 v21, 1, v19
	v_fma_f32 v42, -v20, v19, v18
	v_fma_f32 v43, -v21, v19, v18
	v_cmp_ge_f32_e64 s[2:3], 0, v42
	s_nop 1
	v_cndmask_b32_e64 v19, v19, v20, s[2:3]
	v_cmp_lt_f32_e64 s[2:3], 0, v43
	s_nop 1
	v_cndmask_b32_e64 v19, v19, v21, s[2:3]
	v_mul_f32_e32 v20, 0x37800000, v19
	v_cndmask_b32_e32 v19, v19, v20, vcc
	v_cmp_class_f32_e32 vcc, v18, v245
	s_nop 1
	v_cndmask_b32_e32 v18, v19, v18, vcc
	v_div_scale_f32 v19, s[2:3], v18, v18, 1.0
	v_rcp_f32_e32 v21, v19
	v_div_scale_f32 v20, vcc, 1.0, v18, 1.0
	v_fma_f32 v42, -v19, v21, 1.0
	v_fmac_f32_e32 v21, v42, v21
	v_mul_f32_e32 v42, v20, v21
	v_fma_f32 v43, -v19, v42, v20
	v_fmac_f32_e32 v42, v43, v21
	v_fma_f32 v19, -v19, v42, v20
	v_div_fmas_f32 v19, v19, v21, v42
	v_div_fixup_f32 v42, v19, v18, 1.0
	v_pk_mul_f32 v[18:19], v[42:43], v[32:33] op_sel_hi:[0,1]
	v_pk_mul_f32 v[14:15], v[42:43], v[14:15] op_sel_hi:[0,1]
	v_pk_mul_f32 v[30:31], v[42:43], v[30:31] op_sel_hi:[0,1]
	v_pk_mul_f32 v[20:21], v[42:43], v[16:17] op_sel_hi:[0,1]
	v_pk_mul_f32 v[16:17], v[56:57], v[14:15]
	v_pk_mul_f32 v[14:15], v[54:55], v[18:19]
	v_pk_mul_f32 v[20:21], v[60:61], v[20:21]
	v_pk_mul_f32 v[18:19], v[58:59], v[30:31]
	global_store_dwordx4 v[6:7], v[14:17], off offset:-2064
	global_store_dwordx4 v[6:7], v[18:21], off offset:-2048
	v_pk_mul_f32 v[22:23], v[42:43], v[40:41] op_sel_hi:[0,1]
	v_pk_mul_f32 v[24:25], v[42:43], v[38:39] op_sel_hi:[0,1]
	v_cmp_lt_i32_e32 vcc, s80, v1
	v_pk_mul_f32 v[26:27], v[42:43], v[36:37] op_sel_hi:[0,1]
	v_pk_mul_f32 v[28:29], v[42:43], v[34:35] op_sel_hi:[0,1]
	s_or_b64 s[12:13], vcc, s[12:13]
	v_pk_mul_f32 v[14:15], v[62:63], v[24:25]
	v_pk_mul_f32 v[16:17], v[64:65], v[22:23]
	v_pk_mul_f32 v[18:19], v[66:67], v[28:29]
	v_pk_mul_f32 v[20:21], v[68:69], v[26:27]
	global_store_dwordx4 v[6:7], v[14:17], off offset:-16
	global_store_dwordx4 v[6:7], v[18:21], off
	v_lshl_add_u64 v[6:7], v[6:7], 0, s[10:11]
	s_andn2_b64 exec, exec, s[12:13]
	s_cbranch_execnz .LBB0_845
